# spread the 4 LDS-DMA issues per tile across PV MFMA gaps 0,2,7,10 in attention main loop (was one burst)
# baseline (speedup 1.0000x reference)
; #define AT_WAIT_BAR(N) asm volatile("s_waitcnt vmcnt(" #N ") lgkmcnt(0)\n\ts_barrier" ::: "memory")
; #define AT_ROT() do { sl_prev = sl_cur; sl_cur = sl_next; sl_next = (sl_next == 2) ? 0 : sl_next + 1; } while (0)
; __device__ __forceinline__ void attn_unit(LAS unsigned char* lds, const bf16_t* Qb, const bf16_t* Kb, const bf16_t* Vb, bf16_t* mix,
;                                           int b, int head, int qbase  , float lam, float post_scale, const float* subg) {
;     ...
;     int t = 1;
;     for (; t + 5 < NT; t += 2) {
;         AT_STEP(pB0, pB1, pA0, pA1, t, true, true, true);     AT_WAIT_BAR(4); AT_ROT();
;         AT_STEP(pA0, pA1, pB0, pB1, t + 1, true, true, true); AT_WAIT_BAR(4); AT_ROT();
.LBB0_340:
	s_add_i32 s22, s20, 0xffffc000
	s_and_b32 s22, s22, 0xc000
	v_add_u32_e32 v96, s22, v173
	ds_read_b128 v[164:167], v96 offset:4096
	ds_read_b128 v[182:185], v96 offset:4608
	ds_read_b128 v[186:189], v96 offset:6144
	ds_read_b128 v[190:193], v96 offset:6656
	s_lshl_b32 s16, s16, 14
	s_add_i32 s16, s16, 0
	v_add_f32_e32 v96, v177, v80
	v_cvt_pk_bf16_f32 v160, v80, v79
	v_cvt_pk_bf16_f32 v161, v88, v87
	s_waitcnt lgkmcnt(7)
	v_mfma_f32_32x32x16_bf16 v[112:127], v[156:159], v[140:143], 0
	v_add_f32_e32 v96, v96, v79
	v_add_f32_e32 v96, v96, v88
	v_add_f32_e32 v96, v96, v87
	v_add_f32_e32 v79, v96, v82
	v_cvt_pk_bf16_f32 v162, v82, v83
	v_cvt_pk_bf16_f32 v163, v92, v91
	s_waitcnt lgkmcnt(6)
	v_mfma_f32_32x32x16_bf16 v[96:111], v[148:151], v[140:143], 0
	v_add_f32_e32 v79, v79, v83
	v_add_f32_e32 v79, v79, v92
	v_add_f32_e32 v79, v79, v91
	v_add_f32_e32 v79, v79, v76
	s_waitcnt lgkmcnt(5)
	v_mfma_f32_32x32x16_bf16 v[112:127], v[152:155], v[136:139], v[112:127]
	v_add_f32_e32 v79, v79, v75
	v_cvt_pk_bf16_f32 v148, v76, v75
	v_cvt_pk_bf16_f32 v149, v86, v85
	v_add_f32_e32 v79, v79, v86
	v_add_f32_e32 v79, v79, v85
	v_add_f32_e32 v75, v79, v74
	s_waitcnt lgkmcnt(4)
	v_mfma_f32_32x32x16_bf16 v[96:111], v[144:147], v[136:139], v[96:111]
	v_add_f32_e32 v75, v75, v93
	v_cvt_pk_bf16_f32 v150, v74, v93
	v_cvt_pk_bf16_f32 v151, v94, v95
	v_add_f32_e32 v75, v75, v94
	v_add_f32_e32 v75, v75, v95
	v_add_f32_e32 v74, v75, v84
	s_waitcnt lgkmcnt(3)
	v_mfma_f32_32x32x16_bf16 v[112:127], v[164:167], v[132:135], v[112:127]
	v_add_f32_e32 v74, v74, v81
	v_add_f32_e32 v74, v74, v90
	v_add_f32_e32 v76, v74, v89
	v_cvt_pk_bf16_f32 v74, v84, v81
	v_cvt_pk_bf16_f32 v75, v90, v89
	v_add_f32_e32 v76, v76, v72
	s_waitcnt lgkmcnt(2)
	v_mfma_f32_32x32x16_bf16 v[96:111], v[182:185], v[132:135], v[96:111]
	v_add_f32_e32 v76, v76, v73
	v_add_f32_e32 v76, v76, v78
	v_add_f32_e32 v82, v76, v77
	v_cvt_pk_bf16_f32 v76, v72, v73
	v_cvt_pk_bf16_f32 v77, v78, v77
	v_add_u32_e32 v83, s16, v170
	v_add_u32_e32 v144, s16, v171
	ds_read_b64_tr_b16 v[78:79], v83
	ds_read_b64_tr_b16 v[80:81], v144
	ds_read_b64_tr_b16 v[86:87], v144 offset:512
	ds_read_b64_tr_b16 v[84:85], v83 offset:512
	v_add_f32_e32 v72, v82, v68
	s_waitcnt lgkmcnt(5)
	v_mfma_f32_32x32x16_bf16 v[112:127], v[186:189], v[128:131], v[112:127]
	v_add_f32_e32 v72, v72, v69
	v_cvt_pk_bf16_f32 v68, v68, v69
	v_cvt_pk_bf16_f32 v69, v70, v71
	v_add_f32_e32 v72, v72, v70
	v_add_f32_e32 v72, v72, v71
	v_add_f32_e32 v70, v72, v64
	s_waitcnt lgkmcnt(4)
	v_mfma_f32_32x32x16_bf16 v[96:111], v[190:193], v[128:131], v[96:111]
	v_add_f32_e32 v70, v70, v65
	v_add_f32_e32 v70, v70, v66
	v_add_f32_e32 v72, v70, v67
	v_cvt_pk_bf16_f32 v70, v64, v65
	v_cvt_pk_bf16_f32 v71, v66, v67
	v_add_f32_e32 v82, v174, v72
	s_waitcnt lgkmcnt(2)
	v_mfma_f32_32x32x16_bf16 v[48:63], v[78:81], v[160:163], v[48:63]
	ds_read_b64_tr_b16 v[64:65], v83 offset:1024
	ds_read_b64_tr_b16 v[66:67], v144 offset:1024
	s_add_i32 s16, s20, 0x8000
	s_and_b32 s23, s16, 0xc000
	s_add_i32 s23, s23, s46
	s_add_i32 s24, s23, 0
	s_add_u32 s25, s0, s49
	s_addc_u32 s26, s1, 0
	s_add_u32 s28, s25, 0x9d08000
	s_addc_u32 s29, s26, 0
	s_mov_b32 s27, m0
	s_mov_b32 m0, s24
	s_nop 0
	global_load_lds_dwordx4 v172, s[28:29]
	s_mov_b32 m0, s27
	v_exp_f32_e32 v156, v112
	v_exp_f32_e32 v157, v113
	s_waitcnt lgkmcnt(2)
	v_mfma_f32_32x32x16_bf16 v[32:47], v[84:87], v[160:163], v[32:47]
	ds_read_b64_tr_b16 v[78:79], v83 offset:1536
	ds_read_b64_tr_b16 v[80:81], v144 offset:1536
	v_exp_f32_e32 v158, v114
	v_exp_f32_e32 v159, v115
	s_waitcnt lgkmcnt(2)
	v_mfma_f32_32x32x16_bf16 v[16:31], v[64:67], v[160:163], v[16:31]
	ds_read_b64_tr_b16 v[84:85], v83 offset:4096
	ds_read_b64_tr_b16 v[86:87], v144 offset:4096
	s_add_u32 s28, s25, 0x9e10000
	s_addc_u32 s29, s26, 0
	s_add_i32 s24, 0, 0x2000
	s_add_i32 s23, s23, s24
	s_mov_b32 s27, m0
	s_mov_b32 m0, s23
	s_nop 0
	global_load_lds_dwordx4 v172, s[28:29]
	s_mov_b32 m0, s27
	v_exp_f32_e32 v164, v116
	v_exp_f32_e32 v165, v117
	s_waitcnt lgkmcnt(2)
	v_mfma_f32_32x32x16_bf16 v[0:15], v[78:81], v[160:163], v[0:15]
	ds_read_b64_tr_b16 v[88:89], v83 offset:4608
	ds_read_b64_tr_b16 v[90:91], v144 offset:4608
	v_exp_f32_e32 v160, v118
	v_exp_f32_e32 v161, v119
	s_and_b32 s23, s20, 0xc000
	v_add_u32_e32 v152, s23, v173
	ds_read_b128 v[92:95], v152
	ds_read_b128 v[78:81], v152 offset:512
	s_waitcnt lgkmcnt(4)
	v_mfma_f32_32x32x16_bf16 v[48:63], v[84:87], v[148:151], v[48:63]
	ds_read_b64_tr_b16 v[112:113], v83 offset:5120
	ds_read_b64_tr_b16 v[114:115], v144 offset:5120
	v_exp_f32_e32 v162, v120
	v_exp_f32_e32 v163, v121
	ds_read_b128 v[84:87], v152 offset:2048
	ds_read_b128 v[64:67], v152 offset:2560
	s_waitcnt lgkmcnt(6)
	v_mfma_f32_32x32x16_bf16 v[32:47], v[88:91], v[148:151], v[32:47]
	ds_read_b64_tr_b16 v[116:117], v83 offset:5632
	ds_read_b64_tr_b16 v[118:119], v144 offset:5632
	v_exp_f32_e32 v166, v122
	v_exp_f32_e32 v167, v123
	s_waitcnt lgkmcnt(4)
	v_mfma_f32_32x32x16_bf16 v[16:31], v[112:115], v[148:151], v[16:31]
	ds_read_b64_tr_b16 v[88:89], v83 offset:8192
	ds_read_b64_tr_b16 v[90:91], v144 offset:8192
	v_exp_f32_e32 v174, v124
	v_exp_f32_e32 v175, v125
	s_waitcnt lgkmcnt(2)
	v_mfma_f32_32x32x16_bf16 v[0:15], v[116:119], v[148:151], v[0:15]
	ds_read_b64_tr_b16 v[112:113], v83 offset:8704
	ds_read_b64_tr_b16 v[114:115], v144 offset:8704
	s_lshl_b32 s23, s19, 14
	s_add_i32 s23, s23, s17
	s_add_i32 s29, s23, 0
	s_add_u32 s27, s14, s49
	s_addc_u32 s28, s15, 0
	s_add_u32 s30, s27, 0xae08000
	s_addc_u32 s31, s28, 0
	s_mov_b32 s52, m0
	s_mov_b32 m0, s29
	s_nop 0
	global_load_lds_dwordx4 v172, s[30:31]
	s_mov_b32 m0, s52
	v_exp_f32_e32 v176, v126
	v_exp_f32_e32 v182, v127
	s_waitcnt lgkmcnt(2)
; #define AT_WAIT_BAR(N) asm volatile("s_waitcnt vmcnt(" #N ") lgkmcnt(0)\n\ts_barrier" ::: "memory")
; #define AT_ROT() do { sl_prev = sl_cur; sl_cur = sl_next; sl_next = (sl_next == 2) ? 0 : sl_next + 1; } while (0)
; __device__ __forceinline__ void attn_unit(LAS unsigned char* lds, const bf16_t* Qb, const bf16_t* Kb, const bf16_t* Vb, bf16_t* mix,
;                                           int b, int head, int qbase  , float lam, float post_scale, const float* subg) {
;     ...
;     int t = 1;
;     for (; t + 5 < NT; t += 2) {
;         AT_STEP(pB0, pB1, pA0, pA1, t, true, true, true);     AT_WAIT_BAR(4); AT_ROT();
;         AT_STEP(pA0, pA1, pB0, pB1, t + 1, true, true, true); AT_WAIT_BAR(4); AT_ROT();
	v_mfma_f32_32x32x16_bf16 v[48:63], v[88:91], v[74:77], v[48:63]
	ds_read_b64_tr_b16 v[116:117], v83 offset:9216
	ds_read_b64_tr_b16 v[118:119], v144 offset:9216
	v_exp_f32_e32 v183, v96
	v_exp_f32_e32 v184, v97
	s_waitcnt lgkmcnt(2)
	v_mfma_f32_32x32x16_bf16 v[32:47], v[112:115], v[74:77], v[32:47]
	ds_read_b64_tr_b16 v[88:89], v83 offset:9728
	ds_read_b64_tr_b16 v[90:91], v144 offset:9728
	v_exp_f32_e32 v185, v98
	v_exp_f32_e32 v186, v99
	s_waitcnt lgkmcnt(2)
	v_mfma_f32_32x32x16_bf16 v[16:31], v[116:119], v[74:77], v[16:31]
	ds_read_b64_tr_b16 v[96:97], v83 offset:12288
	ds_read_b64_tr_b16 v[98:99], v144 offset:12288
	s_add_u32 s30, s27, 0xae0a000
	s_addc_u32 s31, s28, 0
	s_add_i32 s23, s23, s24
	s_mov_b32 s29, m0
	s_mov_b32 m0, s23
	s_nop 0
	global_load_lds_dwordx4 v172, s[30:31]
	s_mov_b32 m0, s29
	v_exp_f32_e32 v187, v100
	v_exp_f32_e32 v188, v101
	s_waitcnt lgkmcnt(2)
	v_mfma_f32_32x32x16_bf16 v[0:15], v[88:91], v[74:77], v[0:15]
	ds_read_b64_tr_b16 v[112:113], v83 offset:12800
	ds_read_b64_tr_b16 v[114:115], v144 offset:12800
	v_exp_f32_e32 v76, v102
	v_exp_f32_e32 v77, v103
	s_waitcnt lgkmcnt(2)
	v_mfma_f32_32x32x16_bf16 v[48:63], v[96:99], v[68:71], v[48:63]
	ds_read_b64_tr_b16 v[72:73], v83 offset:13312
	ds_read_b64_tr_b16 v[74:75], v144 offset:13312
	v_exp_f32_e32 v189, v104
	v_exp_f32_e32 v190, v105
	s_waitcnt lgkmcnt(2)
	v_mfma_f32_32x32x16_bf16 v[32:47], v[112:115], v[68:71], v[32:47]
	ds_read_b64_tr_b16 v[88:89], v83 offset:13824
	ds_read_b64_tr_b16 v[90:91], v144 offset:13824
	v_exp_f32_e32 v83, v106
	v_exp_f32_e32 v191, v107
	s_waitcnt lgkmcnt(2)
	v_mfma_f32_32x32x16_bf16 v[16:31], v[72:75], v[68:71], v[16:31]
	v_exp_f32_e32 v192, v108
	v_exp_f32_e32 v193, v109
	s_waitcnt lgkmcnt(0)
	v_mfma_f32_32x32x16_bf16 v[0:15], v[88:91], v[68:71], v[0:15]
	v_exp_f32_e32 v194, v110
	v_exp_f32_e32 v195, v111
	s_waitcnt vmcnt(4) lgkmcnt(0)
	s_barrier
	s_add_i32 s23, s19, 1
	s_cmp_lg_u32 s19, 2
	s_cselect_b32 s23, s23, 0
	ds_read_b128 v[88:91], v152 offset:4096
	ds_read_b128 v[144:147], v152 offset:4608
	ds_read_b128 v[148:151], v152 offset:6144
	ds_read_b128 v[152:155], v152 offset:6656
	s_lshl_b32 s21, s21, 14
	s_add_i32 s21, s21, 0
	v_add_f32_e32 v68, v177, v156
	v_mfma_f32_32x32x16_bf16 v[112:127], v[92:95], v[140:143], 0
	v_add_f32_e32 v68, v68, v157
	v_cvt_pk_bf16_f32 v72, v156, v157
	v_cvt_pk_bf16_f32 v73, v158, v159
	v_add_f32_e32 v68, v68, v158
	v_add_f32_e32 v68, v68, v159
	v_add_f32_e32 v68, v68, v164
	v_cvt_pk_bf16_f32 v74, v164, v165
	v_cvt_pk_bf16_f32 v75, v160, v161
	v_mfma_f32_32x32x16_bf16 v[96:111], v[78:81], v[140:143], 0
	v_add_f32_e32 v68, v68, v165
	v_add_f32_e32 v68, v68, v160
	v_add_f32_e32 v68, v68, v161
	v_add_f32_e32 v68, v68, v162
	v_mfma_f32_32x32x16_bf16 v[112:127], v[84:87], v[136:139], v[112:127]
	v_add_f32_e32 v68, v68, v163
	v_add_f32_e32 v68, v68, v166
	v_add_f32_e32 v70, v68, v167
	v_cvt_pk_bf16_f32 v68, v162, v163
	v_cvt_pk_bf16_f32 v69, v166, v167
	v_mfma_f32_32x32x16_bf16 v[96:111], v[64:67], v[136:139], v[96:111]
	v_add_f32_e32 v64, v70, v174
	v_cvt_pk_bf16_f32 v70, v174, v175
	v_cvt_pk_bf16_f32 v71, v176, v182
	v_add_f32_e32 v64, v64, v175
	v_add_f32_e32 v64, v64, v176
	v_add_f32_e32 v64, v64, v182
	v_add_f32_e32 v64, v64, v183
	s_waitcnt lgkmcnt(3)
	v_mfma_f32_32x32x16_bf16 v[112:127], v[88:91], v[132:135], v[112:127]
	v_add_f32_e32 v64, v64, v184
	v_add_f32_e32 v64, v64, v185
	v_add_f32_e32 v66, v64, v186
	v_cvt_pk_bf16_f32 v64, v183, v184
	v_cvt_pk_bf16_f32 v65, v185, v186
	v_add_f32_e32 v66, v66, v187
	s_waitcnt lgkmcnt(2)
	v_mfma_f32_32x32x16_bf16 v[96:111], v[144:147], v[132:135], v[96:111]
	v_add_f32_e32 v66, v66, v188
	v_add_f32_e32 v66, v66, v76
	v_add_f32_e32 v80, v66, v77
	v_cvt_pk_bf16_f32 v66, v187, v188
	v_cvt_pk_bf16_f32 v67, v76, v77
	v_add_u32_e32 v175, s21, v170
	v_add_u32_e32 v176, s21, v171
	ds_read_b64_tr_b16 v[76:77], v175
	ds_read_b64_tr_b16 v[78:79], v176
	ds_read_b64_tr_b16 v[86:87], v176 offset:512
	ds_read_b64_tr_b16 v[84:85], v175 offset:512
	v_add_f32_e32 v80, v80, v189
	s_waitcnt lgkmcnt(5)
	v_mfma_f32_32x32x16_bf16 v[112:127], v[148:151], v[128:131], v[112:127]
	v_add_f32_e32 v80, v80, v190
	v_cvt_pk_bf16_f32 v160, v189, v190
	v_cvt_pk_bf16_f32 v161, v83, v191
	v_add_f32_e32 v80, v80, v83
	v_add_f32_e32 v80, v80, v191
	v_add_f32_e32 v80, v80, v192
	s_waitcnt lgkmcnt(4)
	v_mfma_f32_32x32x16_bf16 v[96:111], v[152:155], v[128:131], v[96:111]
	v_add_f32_e32 v80, v80, v193
	v_cvt_pk_bf16_f32 v162, v192, v193
	v_cvt_pk_bf16_f32 v163, v194, v195
	v_add_f32_e32 v80, v80, v194
	v_add_f32_e32 v80, v80, v195
	v_add_f32_e32 v174, v82, v80
	s_waitcnt lgkmcnt(2)
; #define AT_WAIT_BAR(N) asm volatile("s_waitcnt vmcnt(" #N ") lgkmcnt(0)\n\ts_barrier" ::: "memory")
; #define AT_ROT() do { sl_prev = sl_cur; sl_cur = sl_next; sl_next = (sl_next == 2) ? 0 : sl_next + 1; } while (0)
; __device__ __forceinline__ void attn_unit(LAS unsigned char* lds, const bf16_t* Qb, const bf16_t* Kb, const bf16_t* Vb, bf16_t* mix,
;                                           int b, int head, int qbase  , float lam, float post_scale, const float* subg) {
;     ...
;     int t = 1;
;     for (; t + 5 < NT; t += 2) {
;         AT_STEP(pB0, pB1, pA0, pA1, t, true, true, true);     AT_WAIT_BAR(4); AT_ROT();
;         AT_STEP(pA0, pA1, pB0, pB1, t + 1, true, true, true); AT_WAIT_BAR(4); AT_ROT();
;     }
	v_mfma_f32_32x32x16_bf16 v[48:63], v[76:79], v[72:75], v[48:63]
	ds_read_b64_tr_b16 v[90:91], v175 offset:1024
	ds_read_b64_tr_b16 v[92:93], v176 offset:1024
	s_add_i32 s21, s22, s46
	s_add_i32 s22, s21, 0
	s_add_u32 s30, s25, 0x9d0a000
	s_addc_u32 s31, s26, 0
	s_mov_b32 s29, m0
	s_mov_b32 m0, s22
	s_nop 0
	global_load_lds_dwordx4 v172, s[30:31]
	s_mov_b32 m0, s29
	v_exp_f32_e32 v80, v112
	v_exp_f32_e32 v79, v113
	s_waitcnt lgkmcnt(2)
	v_mfma_f32_32x32x16_bf16 v[32:47], v[84:87], v[72:75], v[32:47]
	ds_read_b64_tr_b16 v[144:145], v175 offset:1536
	ds_read_b64_tr_b16 v[146:147], v176 offset:1536
	v_exp_f32_e32 v88, v114
	v_exp_f32_e32 v87, v115
	s_waitcnt lgkmcnt(2)
	v_mfma_f32_32x32x16_bf16 v[16:31], v[90:93], v[72:75], v[16:31]
	ds_read_b64_tr_b16 v[112:113], v175 offset:4096
	ds_read_b64_tr_b16 v[114:115], v176 offset:4096
	s_add_u32 s30, s25, 0x9e12000
	s_addc_u32 s31, s26, 0
	s_add_i32 s21, s21, s24
	s_mov_b32 s22, m0
	s_mov_b32 m0, s21
	s_nop 0
	global_load_lds_dwordx4 v172, s[30:31]
	s_mov_b32 m0, s22
	v_exp_f32_e32 v82, v116
	v_exp_f32_e32 v83, v117
	s_waitcnt lgkmcnt(2)
	v_mfma_f32_32x32x16_bf16 v[0:15], v[144:147], v[72:75], v[0:15]
	ds_read_b64_tr_b16 v[164:165], v175 offset:4608
	ds_read_b64_tr_b16 v[166:167], v176 offset:4608
	v_exp_f32_e32 v92, v118
	v_exp_f32_e32 v91, v119
	s_addk_i32 s20, 0x4000
	s_and_b32 s20, s20, 0xc000
	v_add_u32_e32 v72, s20, v173
	ds_read_b128 v[156:159], v72
	ds_read_b128 v[148:151], v72 offset:512
	s_waitcnt lgkmcnt(4)
	v_mfma_f32_32x32x16_bf16 v[48:63], v[112:115], v[68:71], v[48:63]
	ds_read_b64_tr_b16 v[116:117], v175 offset:5120
	ds_read_b64_tr_b16 v[118:119], v176 offset:5120
	v_exp_f32_e32 v76, v120
	v_exp_f32_e32 v75, v121
	ds_read_b128 v[152:155], v72 offset:2048
	ds_read_b128 v[144:147], v72 offset:2560
	s_waitcnt lgkmcnt(6)
	v_mfma_f32_32x32x16_bf16 v[32:47], v[164:167], v[68:71], v[32:47]
	ds_read_b64_tr_b16 v[112:113], v175 offset:5632
	ds_read_b64_tr_b16 v[114:115], v176 offset:5632
	v_exp_f32_e32 v86, v122
	v_exp_f32_e32 v85, v123
	s_waitcnt lgkmcnt(4)
	v_mfma_f32_32x32x16_bf16 v[16:31], v[116:119], v[68:71], v[16:31]
	ds_read_b64_tr_b16 v[120:121], v175 offset:8192
	ds_read_b64_tr_b16 v[122:123], v176 offset:8192
	v_exp_f32_e32 v74, v124
	v_exp_f32_e32 v93, v125
	s_waitcnt lgkmcnt(2)
	v_mfma_f32_32x32x16_bf16 v[0:15], v[112:115], v[68:71], v[0:15]
	ds_read_b64_tr_b16 v[116:117], v175 offset:8704
	ds_read_b64_tr_b16 v[118:119], v176 offset:8704
	s_lshl_b32 s21, s23, 14
	s_add_i32 s21, s21, s17
	s_add_i32 s22, s21, 0
	s_add_u32 s30, s27, 0xae0c000
	s_addc_u32 s31, s28, 0
	s_mov_b32 s25, m0
	s_mov_b32 m0, s22
	s_nop 0
	global_load_lds_dwordx4 v172, s[30:31]
	s_mov_b32 m0, s25
	v_exp_f32_e32 v94, v126
	v_exp_f32_e32 v95, v127
	s_waitcnt lgkmcnt(2)
	v_mfma_f32_32x32x16_bf16 v[48:63], v[120:123], v[64:67], v[48:63]
	ds_read_b64_tr_b16 v[68:69], v175 offset:9216
	ds_read_b64_tr_b16 v[70:71], v176 offset:9216
	v_exp_f32_e32 v84, v96
	v_exp_f32_e32 v81, v97
	s_waitcnt lgkmcnt(2)
	v_mfma_f32_32x32x16_bf16 v[32:47], v[116:119], v[64:67], v[32:47]
	ds_read_b64_tr_b16 v[112:113], v175 offset:9728
	ds_read_b64_tr_b16 v[114:115], v176 offset:9728
	v_exp_f32_e32 v90, v98
	v_exp_f32_e32 v89, v99
	s_waitcnt lgkmcnt(2)
	v_mfma_f32_32x32x16_bf16 v[16:31], v[68:71], v[64:67], v[16:31]
	ds_read_b64_tr_b16 v[96:97], v175 offset:12288
	ds_read_b64_tr_b16 v[98:99], v176 offset:12288
	s_add_u32 s26, s27, 0xae0e000
	s_addc_u32 s27, s28, 0
	s_add_i32 s21, s21, s24
	s_mov_b32 s22, m0
	s_mov_b32 m0, s21
	s_nop 0
	global_load_lds_dwordx4 v172, s[26:27]
	s_mov_b32 m0, s22
	v_exp_f32_e32 v72, v100
	v_exp_f32_e32 v73, v101
	s_waitcnt lgkmcnt(2)
	v_mfma_f32_32x32x16_bf16 v[0:15], v[112:115], v[64:67], v[0:15]
	ds_read_b64_tr_b16 v[116:117], v175 offset:12800
	ds_read_b64_tr_b16 v[118:119], v176 offset:12800
	v_exp_f32_e32 v78, v102
	v_exp_f32_e32 v77, v103
	s_waitcnt lgkmcnt(2)
	v_mfma_f32_32x32x16_bf16 v[48:63], v[96:99], v[160:163], v[48:63]
	ds_read_b64_tr_b16 v[64:65], v175 offset:13312
	ds_read_b64_tr_b16 v[66:67], v176 offset:13312
	v_exp_f32_e32 v68, v104
	v_exp_f32_e32 v69, v105
	s_waitcnt lgkmcnt(2)
	v_mfma_f32_32x32x16_bf16 v[32:47], v[116:119], v[160:163], v[32:47]
	ds_read_b64_tr_b16 v[96:97], v175 offset:13824
	ds_read_b64_tr_b16 v[98:99], v176 offset:13824
	v_exp_f32_e32 v70, v106
	v_exp_f32_e32 v71, v107
	s_waitcnt lgkmcnt(2)
	v_mfma_f32_32x32x16_bf16 v[16:31], v[64:67], v[160:163], v[16:31]
	v_exp_f32_e32 v64, v108
	v_exp_f32_e32 v65, v109
	s_waitcnt lgkmcnt(0)
	v_mfma_f32_32x32x16_bf16 v[0:15], v[96:99], v[160:163], v[0:15]
	v_exp_f32_e32 v66, v110
	v_exp_f32_e32 v67, v111
	s_add_i32 s22, s23, 1
	s_cmp_lg_u32 s23, 2
	s_mov_b32 s20, s16
	s_mov_b32 s16, s19
	s_cselect_b32 s19, s22, 0
	s_add_i32 s18, s18, 2
	s_add_u32 s14, s14, 0x8000
	s_addc_u32 s15, s15, 0
	s_waitcnt vmcnt(4) lgkmcnt(0)
	s_barrier
	s_add_u32 s0, s0, 0x4000
	s_addc_u32 s1, s1, 0
	s_mov_b32 s21, s23
	s_cmpk_gt_u32 s18, 0x7c
	s_cbranch_scc0 .LBB0_340
	s_movk_i32 s53, 0x7f
	s_branch .LBB0_343
